# sparse attention tile loop: hipcc's two boolean-materialisation ballots (v_cndmask + v_cmp_ne) replaced by one s_andn2_b64 each
# baseline (speedup 1.0000x reference)
.LBB0_78:
	s_or_b64 exec, exec, s[0:1]
	s_andn2_b64 s[0:1], exec, s[8:9]
	s_andn2_b64 vcc, exec, s[8:9]
	s_mul_i32 s48, s45, 0x8c00
	s_cbranch_vccnz .LBB0_80
	s_add_i32 s8, s48, 0
	v_add3_u32 v174, s8, v179, v181
	ds_write_b128 v174, v[130:133]
	v_add3_u32 v174, s8, v206, v181
	ds_write_b128 v174, v[134:137]
	v_add3_u32 v174, s8, v207, v163
	v_add_u32_e32 v174, 0x4000, v174
	ds_write2_b64 v174, v[138:139], v[140:141] offset0:128 offset1:130
	v_add3_u32 v174, s8, v208, v163
	v_add_u32_e32 v174, 0x4000, v174
	ds_write2_b64 v174, v[142:143], v[144:145] offset0:128 offset1:130
.LBB0_80:
	s_add_i32 s8, s45, 1
	s_cmp_lg_u32 s45, 2
	s_cselect_b32 s50, s8, 0
	s_and_b64 vcc, exec, s[0:1]
	s_waitcnt lgkmcnt(0)
	s_barrier
	s_cbranch_vccnz .LBB0_61
	s_andn2_b64 s[8:9], exec, s[30:31]
	s_andn2_b64 vcc, exec, s[30:31]
	s_waitcnt vmcnt(0)
	v_mov_b64_e32 v[202:203], v[204:205]
	s_cbranch_vccnz .LBB0_83
	global_load_dwordx2 v[202:203], v[196:197], off offset:8
